# grid syncs 2-6: cooperative-groups barrier replaced by flat monotonic counter barrier (wbl2 release, sc1 poll, inv acquire), census-guarded with original fallback, bounded spin
# speedup vs baseline: 1.0113x; 1.0113x over previous
; DI int lane_id_() { int l = __builtin_amdgcn_mbcnt_hi(-1, __builtin_amdgcn_mbcnt_lo(-1, 0)); asm volatile("" : "+v"(l)); return l; }
; DI void local_barrier(unsigned* ctr, unsigned target, int ws) {
;   asm volatile("s_waitcnt vmcnt(0)" ::: "memory");
;   __syncthreads();
;   if (ws == 0 && lane_id_() == 0) {
;     __hip_atomic_fetch_add(ctr, 1u, __ATOMIC_RELAXED, __HIP_MEMORY_SCOPE_AGENT);
;     unsigned sp = 0;
;     while (__hip_atomic_load(ctr, __ATOMIC_RELAXED, __HIP_MEMORY_SCOPE_AGENT) < target) {
;       __builtin_amdgcn_s_sleep(1);
;       if (++sp > (1u << 22)) break;
;     }
;     __builtin_amdgcn_fence(__ATOMIC_ACQUIRE, "agent");
;     asm volatile("s_waitcnt vmcnt(0)" ::: "memory");
;   }
;   __syncthreads();
; __global__ void __launch_bounds__(NTHR) fwd_kernel(Params pk) {
;     ...
;           grid.sync();
.LBB0_440:
	s_barrier
	s_and_saveexec_b64 s[10:11], s[88:89]
	s_cbranch_execz .LBB0_450
	v_readlane_b32 s14, v255, 3
	v_readlane_b32 s15, v255, 4
	s_and_b64 vcc, exec, s[14:15]
	s_cbranch_vccnz .Lgs1_orig
	buffer_wbl2 sc1
	s_waitcnt vmcnt(0)
	s_add_u32 s12, s96, 0xfffffae8
	s_addc_u32 s13, s97, -1
	s_load_dwordx2 s[12:13], s[12:13], 0x0
	v_mov_b32_e32 v2, 0
	v_mov_b32_e32 v0, 1
	s_mov_b32 s14, 0x100
	s_movk_i32 s15, 0x4000
	s_waitcnt lgkmcnt(0)
	global_atomic_add v2, v0, s[12:13] offset:2044
.Lgs1_poll:
	global_load_dword v0, v2, s[12:13] offset:2044 sc1
	s_waitcnt vmcnt(0)
	v_cmp_le_u32_e32 vcc, s14, v0
	s_cbranch_vccnz .Lgs1_inv
	s_sleep 1
	s_add_i32 s15, s15, -1
	s_cmp_eq_u32 s15, 0
	s_cbranch_scc0 .Lgs1_poll
.Lgs1_inv:
	buffer_inv sc1
	s_waitcnt vmcnt(0)
	s_branch .Lgs1_end
.Lgs1_orig:
	buffer_wbl2 sc1
	s_waitcnt vmcnt(0)
	s_load_dwordx2 s[12:13], s[96:97], 0x58
	v_mov_b32_e32 v2, 0
	s_mov_b64 s[14:15], exec
	v_mbcnt_lo_u32_b32 v1, s14, 0
	v_mbcnt_hi_u32_b32 v1, s15, v1
	s_waitcnt lgkmcnt(0)
	global_load_dword v0, v2, s[12:13] offset:40
	v_cmp_eq_u32_e32 vcc, 0, v1
	s_and_saveexec_b64 s[16:17], vcc
	s_cbranch_execz .LBB0_443
	s_bcnt1_i32_b64 s0, s[14:15]
	v_mov_b32_e32 v3, s0
	global_atomic_add v3, v2, v3, s[12:13] offset:32 sc0

; DI void kprep0_phase(int ws, PP p, char* shm) {
;     ...
;   for (int item = blockIdx.x; item < 256; item += gridDim.x) {
;     const int b = item >> 6, n = (item >> 1) & 31, hg = item & 1;
;     const int cc = tid & 31, tg = tid >> 5, head = hg * 4 + (cc >> 3), dch = cc & 7;
;     float sum[8];
; #pragma unroll
;     for (int e = 0; e < 8; ++e) sum[e] = 0.f;
; #pragma unroll 1
;     for (int tb = 0; tb < 16; tb += 8) {
;     u32x4 wv[8];
; #pragma unroll
;     for (int t8 = 0; t8 < 8; ++t8) wv[t8] = *(const u32x4*)(u + ((long)b * SEQ + n * 256 + tg * 16 + tb + t8) * IN0 + 1536 + head * 64 + dch * 8);
; __global__ void __launch_bounds__(NTHR) fwd_kernel(Params pk) {
;     ...
;           grid.sync();
.Lgs1_end:
.LBB0_450:
	s_or_b64 exec, exec, s[10:11]
	s_mov_b64 s[16:17], s[94:95]
	v_mov_b32_e32 v0, v195
	s_barrier
	s_cmpk_gt_i32 s2, 0xff
	v_add_u32_e32 v0, s33, v0
	s_cbranch_scc1 .LBB0_473
	s_load_dwordx2 s[4:5], s[16:17], 0x130
	v_and_b32_e32 v1, 31, v0
	v_ashrrev_i32_e32 v3, 5, v0
	v_and_b32_e32 v4, 7, v0
	s_movk_i32 s0, 0x100
	v_bfe_u32 v92, v0, 3, 2
	v_lshlrev_b32_e32 v36, 4, v3
	v_lshlrev_b32_e32 v2, 3, v4
	v_mov_b32_e32 v39, 0
	v_lshlrev_b32_e32 v3, 10, v3
	v_lshlrev_b32_e32 v1, 5, v1
	v_cmp_gt_i32_e64 s[14:15], s0, v0
	v_lshlrev_b32_e32 v93, 2, v0
	v_ashrrev_i32_e32 v40, 6, v0
	v_and_b32_e32 v0, 63, v0
	v_lshlrev_b32_e32 v38, 4, v4
	v_ashrrev_i32_e32 v37, 31, v36
	v_cmp_gt_u32_e64 s[10:11], 2, v4
	s_mov_b32 s19, 0
	v_cmp_eq_u32_e64 s[12:13], 0, v4
	v_ashrrev_i32_e32 v41, 31, v40
	s_waitcnt lgkmcnt(0)
	v_lshl_add_u64 v[42:43], s[4:5], 0, v[38:39]
	s_movk_i32 s0, 0x1400
	v_mov_b64_e32 v[44:45], s[4:5]
	v_lshlrev_b32_e32 v46, 1, v2
	v_mov_b32_e32 v47, v39
	s_movk_i32 s1, 0x2000
	s_movk_i32 s3, 0x3000
	s_movk_i32 s4, 0x4000
	s_movk_i32 s5, 0x5000
	s_movk_i32 s6, 0x7000
	s_mov_b32 s7, 0x8000
	s_mov_b32 s8, 0x9000
	v_add_u32_e32 v94, v3, v1
	v_lshlrev_b32_e32 v48, 2, v0
	s_mov_b32 s9, s2
	s_branch .LBB0_453

; DI int lane_id_() { int l = __builtin_amdgcn_mbcnt_hi(-1, __builtin_amdgcn_mbcnt_lo(-1, 0)); asm volatile("" : "+v"(l)); return l; }
; DI void local_barrier(unsigned* ctr, unsigned target, int ws) {
;   asm volatile("s_waitcnt vmcnt(0)" ::: "memory");
;   __syncthreads();
;   if (ws == 0 && lane_id_() == 0) {
;     __hip_atomic_fetch_add(ctr, 1u, __ATOMIC_RELAXED, __HIP_MEMORY_SCOPE_AGENT);
;     unsigned sp = 0;
;     while (__hip_atomic_load(ctr, __ATOMIC_RELAXED, __HIP_MEMORY_SCOPE_AGENT) < target) {
;       __builtin_amdgcn_s_sleep(1);
;       if (++sp > (1u << 22)) break;
;     }
;     __builtin_amdgcn_fence(__ATOMIC_ACQUIRE, "agent");
;     asm volatile("s_waitcnt vmcnt(0)" ::: "memory");
;   }
;   __syncthreads();
; __global__ void __launch_bounds__(NTHR) fwd_kernel(Params pk) {
;     ...
;           grid.sync();
.LBB0_837:
	s_barrier
	s_and_saveexec_b64 s[10:11], s[86:87]
	s_cbranch_execz .LBB0_847
	v_readlane_b32 s14, v255, 3
	v_readlane_b32 s15, v255, 4
	s_and_b64 vcc, exec, s[14:15]
	s_cbranch_vccnz .Lgs2_orig
	buffer_wbl2 sc1
	s_waitcnt vmcnt(0)
	s_add_u32 s12, s96, 0xfffffae8
	s_addc_u32 s13, s97, -1
	s_load_dwordx2 s[12:13], s[12:13], 0x0
	v_mov_b32_e32 v2, 0
	v_mov_b32_e32 v0, 1
	s_mov_b32 s14, 0x200
	s_movk_i32 s15, 0x4000
	s_waitcnt lgkmcnt(0)
	global_atomic_add v2, v0, s[12:13] offset:2044

; template <class Desc, class Epi>
; DI void gemm_phase(int ws, int gx, int gslot, char* shm, int nM, int nN, Desc desc, Epi epi) {
;   const int ntiles = nM * nN;
;   const int G = gridDim.x, bid = blockIdx.x;
;   const bool xcdmap = (G % 8 == 0) && (ntiles % 8 == 0);
;   const int per = ntiles / 8, slots = G / 8;
;   auto tile_at = [&](int i, int& pm, int& pn) -> bool {
;     int t;
;     if (xcdmap) {
;       int lt = gslot + slots * i;
;       if (lt >= per) return false;
;       t = gx * per + lt;
;     } else {
;       t = bid + G * i;
;       if (t >= ntiles) return false;
;     }
;     const int WGM = 8;
;     int nig = WGM * nN, gid = t / nig, fm = gid * WGM, gsz = min(nM - fm, WGM);
;     pm = fm + ((t % nig) % gsz);
;     pn = (t % nig) / gsz;
;     return true;
;   };
;   __syncthreads();
;   int pm, pn;
;   if (!tile_at(0, pm, pn)) return;
;   TileDesc td = desc(pm, pn);
; __global__ void __launch_bounds__(NTHR) fwd_kernel(Params pk) {
;     ...
;           grid.sync();
.Lgs2_end:
.LBB0_847:
	s_or_b64 exec, exec, s[10:11]
	v_readlane_b32 s0, v255, 5
	v_readlane_b32 s1, v255, 6
	s_mov_b64 s[10:11], s[94:95]
	s_and_b64 vcc, exec, s[0:1]
	s_barrier
	s_barrier
	s_cbranch_vccz .LBB0_853
	s_mov_b64 s[14:15], 0
	s_cmpk_lt_i32 s2, 0x200
	s_mov_b64 s[12:13], 0
	s_cbranch_scc0 .LBB0_850
	v_readlane_b32 s0, v255, 1
	s_lshl_b32 s0, s0, 6
	s_mov_b64 s[12:13], -1

; DI int lane_id_() { int l = __builtin_amdgcn_mbcnt_hi(-1, __builtin_amdgcn_mbcnt_lo(-1, 0)); asm volatile("" : "+v"(l)); return l; }
; DI void local_barrier(unsigned* ctr, unsigned target, int ws) {
;   asm volatile("s_waitcnt vmcnt(0)" ::: "memory");
;   __syncthreads();
;   if (ws == 0 && lane_id_() == 0) {
;     __hip_atomic_fetch_add(ctr, 1u, __ATOMIC_RELAXED, __HIP_MEMORY_SCOPE_AGENT);
;     unsigned sp = 0;
;     while (__hip_atomic_load(ctr, __ATOMIC_RELAXED, __HIP_MEMORY_SCOPE_AGENT) < target) {
;       __builtin_amdgcn_s_sleep(1);
;       if (++sp > (1u << 22)) break;
;     }
;     __builtin_amdgcn_fence(__ATOMIC_ACQUIRE, "agent");
;     asm volatile("s_waitcnt vmcnt(0)" ::: "memory");
;   }
;   __syncthreads();
; __global__ void __launch_bounds__(NTHR) fwd_kernel(Params pk) {
;     ...
;           grid.sync();
.LBB0_1456:
	s_barrier
	s_and_saveexec_b64 s[10:11], s[86:87]
	s_cbranch_execz .LBB0_1466
	v_readlane_b32 s14, v255, 3
	v_readlane_b32 s15, v255, 4
	s_and_b64 vcc, exec, s[14:15]
	s_cbranch_vccnz .Lgs3_orig
	buffer_wbl2 sc1
	s_waitcnt vmcnt(0)
	s_add_u32 s12, s96, 0xfffffae8
	s_addc_u32 s13, s97, -1
	s_load_dwordx2 s[12:13], s[12:13], 0x0
	v_mov_b32_e32 v2, 0
	v_mov_b32_e32 v0, 1
	s_mov_b32 s14, 0x300
	s_movk_i32 s15, 0x4000
	s_waitcnt lgkmcnt(0)
	global_atomic_add v2, v0, s[12:13] offset:2044

; __global__ void __launch_bounds__(NTHR) fwd_kernel(Params pk) {
;     ...
;           grid.sync();
.Lgs3_orig:
	buffer_wbl2 sc1
	s_waitcnt vmcnt(0)
	s_load_dwordx2 s[12:13], s[96:97], 0x58
	v_mov_b32_e32 v2, 0
	s_mov_b64 s[14:15], exec
	v_mbcnt_lo_u32_b32 v1, s14, 0
	v_mbcnt_hi_u32_b32 v1, s15, v1
	s_waitcnt lgkmcnt(0)
	global_load_dword v0, v2, s[12:13] offset:40
	v_cmp_eq_u32_e32 vcc, 0, v1
	s_and_saveexec_b64 s[16:17], vcc
	s_cbranch_execz .LBB0_1459
	s_bcnt1_i32_b64 s1, s[14:15]
	v_mov_b32_e32 v3, s1
	global_atomic_add v3, v2, v3, s[12:13] offset:32 sc0

; DI int mytid(int ws) { return launder(ws * 64 + lane_id_()); }
; DI void rope1_phase(int ws, PP p) {
;   const int tid = mytid(ws);
;   u16* u = p->big;
;   for (int e = blockIdx.x * NTHR + tid; e < NT * 4; e += gridDim.x * NTHR) {
;     const int trow = e >> 2, w = e & 3, pos = trow & (SEQ - 1);
;     u16* ptr = u + (long)trow * IN1P + ((w & 2) ? 1536 : 1280) + (w & 1) * 64;
;     u32x4 a = *(const u32x4*)ptr, bq = *(const u32x4*)(ptr + 8);
;     const float* cs = p->rope + pos * 16;
; __global__ void __launch_bounds__(NTHR) fwd_kernel(Params pk) {
;     ...
;           grid.sync();
.Lgs3_end:
.LBB0_1466:
	s_or_b64 exec, exec, s[10:11]
	s_mov_b64 s[16:17], s[94:95]
	v_mov_b32_e32 v0, v195
	s_barrier
	s_mov_b32 s1, 0x20000
	v_add_u32_e32 v0, s33, v0
	s_nop 0
	v_lshl_add_u32 v2, s2, 9, v0
	v_cmp_gt_i32_e32 vcc, s1, v2
	s_and_saveexec_b64 s[10:11], vcc
	s_cbranch_execz .LBB0_1469
	s_load_dwordx2 s[12:13], s[16:17], 0x100
	s_load_dwordx2 s[14:15], s[16:17], 0x130
	v_lshlrev_b32_e32 v0, 6, v0
	s_lshl_b32 s1, s91, 9
	v_lshl_add_u32 v3, s2, 15, v0
	s_lshl_b32 s3, s91, 15
	s_mov_b64 s[16:17], 0
	v_mov_b32_e32 v4, 0xc00
	v_mov_b32_e32 v5, 0xa00
	v_mov_b32_e32 v1, 0
	s_mov_b32 s4, 0x1ffff

; DI int lane_id_() { int l = __builtin_amdgcn_mbcnt_hi(-1, __builtin_amdgcn_mbcnt_lo(-1, 0)); asm volatile("" : "+v"(l)); return l; }
; DI void local_barrier(unsigned* ctr, unsigned target, int ws) {
;   asm volatile("s_waitcnt vmcnt(0)" ::: "memory");
;   __syncthreads();
;   if (ws == 0 && lane_id_() == 0) {
;     __hip_atomic_fetch_add(ctr, 1u, __ATOMIC_RELAXED, __HIP_MEMORY_SCOPE_AGENT);
;     unsigned sp = 0;
;     while (__hip_atomic_load(ctr, __ATOMIC_RELAXED, __HIP_MEMORY_SCOPE_AGENT) < target) {
;       __builtin_amdgcn_s_sleep(1);
;       if (++sp > (1u << 22)) break;
;     }
;     __builtin_amdgcn_fence(__ATOMIC_ACQUIRE, "agent");
;     asm volatile("s_waitcnt vmcnt(0)" ::: "memory");
;   }
;   __syncthreads();
; __global__ void __launch_bounds__(NTHR) fwd_kernel(Params pk) {
;     ...
;           grid.sync();
.LBB0_1557:
	s_barrier
	s_barrier
	s_and_saveexec_b64 s[10:11], s[86:87]
	s_cbranch_execz .LBB0_1567
	v_readlane_b32 s14, v255, 3
	v_readlane_b32 s15, v255, 4
	s_and_b64 vcc, exec, s[14:15]
	s_cbranch_vccnz .Lgs4_orig
	buffer_wbl2 sc1
	s_waitcnt vmcnt(0)
	s_add_u32 s12, s96, 0xfffffae8
	s_addc_u32 s13, s97, -1
	s_load_dwordx2 s[12:13], s[12:13], 0x0
	v_mov_b32_e32 v2, 0
	v_mov_b32_e32 v0, 1
	s_mov_b32 s14, 0x400
	s_movk_i32 s15, 0x4000
	s_waitcnt lgkmcnt(0)
	global_atomic_add v2, v0, s[12:13] offset:2044

; DI int lane_id_() { int l = __builtin_amdgcn_mbcnt_hi(-1, __builtin_amdgcn_mbcnt_lo(-1, 0)); asm volatile("" : "+v"(l)); return l; }
; DI int grab_begin(int ws, unsigned* ctr) {
;   int v = 0;
;   if (ws == 0 && lane_id_() == 0) v = (int)atomicAdd(ctr, 1u);
;   return v;
; __global__ void __launch_bounds__(NTHR) fwd_kernel(Params pk) {
;     ...
;           grid.sync();
.Lgs4_end:
.LBB0_1567:
	s_or_b64 exec, exec, s[10:11]
	s_mov_b64 s[80:81], s[94:95]
	s_and_b64 vcc, exec, s[74:75]
	v_mov_b32_e32 v0, 0
	s_barrier
	s_cbranch_vccnz .LBB0_1573
	v_mov_b32_e32 v1, v195
	v_mov_b32_e32 v0, 0
	v_cmp_eq_u32_e32 vcc, 0, v1
	s_and_saveexec_b64 s[10:11], vcc
	s_cbranch_execz .LBB0_1572
	s_mov_b64 s[14:15], exec
	v_mbcnt_lo_u32_b32 v0, s14, 0
	v_mbcnt_hi_u32_b32 v0, s15, v0
	v_cmp_eq_u32_e32 vcc, 0, v0
	s_and_saveexec_b64 s[12:13], vcc
	s_cbranch_execz .LBB0_1571
	s_bcnt1_i32_b64 s0, s[14:15]
	v_mov_b32_e32 v2, s0
	s_load_dwordx2 s[0:1], s[80:81], 0x160
	v_mov_b32_e32 v1, 0
	s_waitcnt lgkmcnt(0)
	global_atomic_add v1, v1, v2, s[0:1] offset:20 sc0

; DI int lane_id_() { int l = __builtin_amdgcn_mbcnt_hi(-1, __builtin_amdgcn_mbcnt_lo(-1, 0)); asm volatile("" : "+v"(l)); return l; }
; DI void local_barrier(unsigned* ctr, unsigned target, int ws) {
;   asm volatile("s_waitcnt vmcnt(0)" ::: "memory");
;   __syncthreads();
;   if (ws == 0 && lane_id_() == 0) {
;     __hip_atomic_fetch_add(ctr, 1u, __ATOMIC_RELAXED, __HIP_MEMORY_SCOPE_AGENT);
;     unsigned sp = 0;
;     while (__hip_atomic_load(ctr, __ATOMIC_RELAXED, __HIP_MEMORY_SCOPE_AGENT) < target) {
;       __builtin_amdgcn_s_sleep(1);
;       if (++sp > (1u << 22)) break;
;     }
;     __builtin_amdgcn_fence(__ATOMIC_ACQUIRE, "agent");
;     asm volatile("s_waitcnt vmcnt(0)" ::: "memory");
;   }
;   __syncthreads();
; __global__ void __launch_bounds__(NTHR) fwd_kernel(Params pk) {
;     ...
;           grid.sync();
.LBB0_1798:
	s_barrier
	s_mov_b64 s[10:11], exec
	v_readlane_b32 s0, v255, 13
	v_readlane_b32 s1, v255, 14
	v_readlane_b32 s86, v255, 21
	v_readlane_b32 s88, v255, 19
	s_and_b64 s[0:1], s[10:11], s[0:1]
	v_readlane_b32 s87, v255, 22
	v_readlane_b32 s89, v255, 20
	v_readlane_b32 s2, v255, 18
	s_mov_b64 exec, s[0:1]
	s_cbranch_execz .LBB0_1808
	v_readlane_b32 s14, v255, 3
	v_readlane_b32 s15, v255, 4
	s_and_b64 vcc, exec, s[14:15]
	s_cbranch_vccnz .Lgs5_orig
	buffer_wbl2 sc1
	s_waitcnt vmcnt(0)
	s_add_u32 s12, s88, 0xfffffae8
	s_addc_u32 s13, s89, -1
	s_load_dwordx2 s[12:13], s[12:13], 0x0
	v_mov_b32_e32 v2, 0
	v_mov_b32_e32 v0, 1
	s_mov_b32 s14, 0x500
	s_movk_i32 s15, 0x4000
	s_waitcnt lgkmcnt(0)
	global_atomic_add v2, v0, s[12:13] offset:2044

; __global__ void __launch_bounds__(NTHR) fwd_kernel(Params pk) {
;     ...
;           grid.sync();
.Lgs5_orig:
	buffer_wbl2 sc1
	s_waitcnt vmcnt(0)
	s_load_dwordx2 s[12:13], s[88:89], 0x58
	v_mov_b32_e32 v2, 0
	s_mov_b64 s[14:15], exec
	v_mbcnt_lo_u32_b32 v1, s14, 0
	v_mbcnt_hi_u32_b32 v1, s15, v1
	s_waitcnt lgkmcnt(0)
	global_load_dword v0, v2, s[12:13] offset:40
	v_cmp_eq_u32_e32 vcc, 0, v1
	s_and_saveexec_b64 s[16:17], vcc
	s_cbranch_execz .LBB0_1801
	s_bcnt1_i32_b64 s0, s[14:15]
	v_mov_b32_e32 v3, s0
	global_atomic_add v3, v2, v3, s[12:13] offset:32 sc0

; template <class Desc, class Epi>
; DI void gemm_phase(int ws, int gx, int gslot, char* shm, int nM, int nN, Desc desc, Epi epi) {
;   const int ntiles = nM * nN;
;   const int G = gridDim.x, bid = blockIdx.x;
;   const bool xcdmap = (G % 8 == 0) && (ntiles % 8 == 0);
;   const int per = ntiles / 8, slots = G / 8;
;   auto tile_at = [&](int i, int& pm, int& pn) -> bool {
;     int t;
;     if (xcdmap) {
;       int lt = gslot + slots * i;
;       if (lt >= per) return false;
;       t = gx * per + lt;
;     } else {
;       t = bid + G * i;
;       if (t >= ntiles) return false;
;     }
;     const int WGM = 8;
;     int nig = WGM * nN, gid = t / nig, fm = gid * WGM, gsz = min(nM - fm, WGM);
;     pm = fm + ((t % nig) % gsz);
;     pn = (t % nig) / gsz;
;     return true;
;   };
;   __syncthreads();
;   int pm, pn;
;   if (!tile_at(0, pm, pn)) return;
;   TileDesc td = desc(pm, pn);
; __global__ void __launch_bounds__(NTHR) fwd_kernel(Params pk) {
;     ...
;           grid.sync();
.Lgs5_end:
.LBB0_1808:
	s_or_b64 exec, exec, s[10:11]
	v_readlane_b32 s0, v255, 5
	v_readlane_b32 s1, v255, 6
	s_mov_b64 s[10:11], s[86:87]
	s_and_b64 vcc, exec, s[0:1]
	s_barrier
	s_barrier
	s_cbranch_vccz .LBB0_1814
	s_mov_b64 s[14:15], 0
	s_cmpk_lt_i32 s2, 0x200
	s_mov_b64 s[12:13], 0
	s_cbranch_scc0 .LBB0_1811
	v_readlane_b32 s0, v255, 1
	s_lshl_b32 s0, s0, 6
	s_mov_b64 s[12:13], -1
